# MLA: row-max ops spread under the PV MFMAs, cross-half permlane only on the rare rescale path (nothing trails the last MFMA)
# baseline (speedup 1.0000x reference)
.Lmla_loop:
.Lmla_it0:
	s_add_i32 s42, s65, 3
	s_min_u32 s42, s42, s44
	s_lshl_b64 s[6:7], s[42:43], 17
	v_lshl_add_u64 v[242:243], v[190:191], 0, s[6:7]
	s_lshl_b64 s[6:7], s[42:43], 12
	v_lshl_add_u64 v[244:245], v[194:195], 0, s[6:7]
	s_add_i32 s42, s65, 2
	s_min_u32 s42, s42, s44
	s_lshl_b64 s[6:7], s[42:43], 17
	v_lshl_add_u64 v[246:247], v[192:193], 0, s[6:7]
	global_load_dwordx4 v[6:9], v[242:243], off
	global_load_dwordx4 v[10:13], v[246:247], off
	global_load_dwordx4 v[2:5], v[244:245], off
	s_cmp_ge_u32 s65, s45
	s_cbranch_scc1 .Lmla_skip0
	s_add_i32 s41, s65, 1
	s_cmp_ge_u32 s41, s64
	s_cselect_b32 s7, 1, 0
	s_cmp_lt_u32 s41, s45
	s_cselect_b32 s26, 1, 0
	s_and_b32 s56, s7, s26
	s_lshl_b32 s27, s41, 6
	ds_read_b128 v[164:167], v210 offset:25600
	ds_read_b128 v[168:171], v210 offset:25632
	ds_read_b128 v[172:175], v210 offset:25664
	ds_read_b128 v[214:217], v210 offset:25696
	ds_read_b128 v[218:221], v210 offset:25728
	ds_read_b128 v[222:225], v210 offset:25760
	v_exp_f32_e32 v64, v64
	v_exp_f32_e32 v65, v65
	v_exp_f32_e32 v66, v66
	v_exp_f32_e32 v67, v67
	s_waitcnt lgkmcnt(5)
	v_mfma_f32_32x32x16_bf16 v[132:147], v[164:167], v[96:99], v[48:63]
	ds_read_b128 v[164:167], v210 offset:32256
	v_add_f32_e32 v14, v64, v65
	v_add_f32_e32 v15, v66, v67
	v_exp_f32_e32 v68, v68
	v_exp_f32_e32 v69, v69
	s_waitcnt lgkmcnt(5)
	v_mfma_f32_32x32x16_bf16 v[132:147], v[168:171], v[100:103], v[132:147]
	ds_read_b128 v[168:171], v210 offset:32288
	v_exp_f32_e32 v70, v70
	v_exp_f32_e32 v71, v71
	v_add_f32_e32 v14, v14, v15
	v_add_f32_e32 v15, v68, v69
	s_waitcnt lgkmcnt(5)
	v_mfma_f32_32x32x16_bf16 v[132:147], v[172:175], v[104:107], v[132:147]
	ds_read_b128 v[172:175], v210 offset:32320
	v_add_f32_e32 v213, v70, v71
	v_cvt_pk_bf16_f32 v64, v64, v65
	v_cvt_pk_bf16_f32 v65, v66, v67
	v_cvt_pk_bf16_f32 v66, v68, v69
	v_cvt_pk_bf16_f32 v67, v70, v71
	s_waitcnt lgkmcnt(5)
	v_mfma_f32_32x32x16_bf16 v[132:147], v[214:217], v[108:111], v[132:147]
	ds_read_b128 v[214:217], v210 offset:32352
	v_exp_f32_e32 v72, v72
	v_exp_f32_e32 v73, v73
	v_exp_f32_e32 v74, v74
	v_exp_f32_e32 v75, v75
	s_waitcnt lgkmcnt(5)
	v_mfma_f32_32x32x16_bf16 v[132:147], v[218:221], v[112:115], v[132:147]
	ds_read_b128 v[218:221], v210 offset:32384
	v_add_f32_e32 v14, v14, v15
	v_add_f32_e32 v14, v14, v213
	v_exp_f32_e32 v76, v76
	v_exp_f32_e32 v77, v77
	s_waitcnt lgkmcnt(5)
	v_mfma_f32_32x32x16_bf16 v[132:147], v[222:225], v[116:119], v[132:147]
	ds_read_b128 v[222:225], v210 offset:32416
	v_exp_f32_e32 v78, v78
	v_exp_f32_e32 v79, v79
	v_add_f32_e32 v15, v72, v73
	v_add_f32_e32 v213, v74, v75
	s_waitcnt lgkmcnt(5)
	v_mfma_f32_32x32x16_bf16 v[148:163], v[164:167], v[96:99], v[48:63]
	ds_read_b64_tr_b16 v[226:227], v211 offset:13312
	ds_read_b64_tr_b16 v[228:229], v211 offset:14848
	v_add_f32_e32 v248, v76, v77
	v_add_f32_e32 v249, v78, v79
	v_cvt_pk_bf16_f32 v68, v72, v73
	v_cvt_pk_bf16_f32 v69, v74, v75
	v_cvt_pk_bf16_f32 v70, v76, v77
	v_cvt_pk_bf16_f32 v71, v78, v79
	s_waitcnt lgkmcnt(6)
	v_mfma_f32_32x32x16_bf16 v[148:163], v[168:171], v[100:103], v[148:163]
	ds_read_b64_tr_b16 v[230:231], v211 offset:13376
	ds_read_b64_tr_b16 v[232:233], v211 offset:14912
	v_add_f32_e32 v15, v15, v213
	v_add_f32_e32 v248, v248, v249
	v_exp_f32_e32 v80, v80
	v_exp_f32_e32 v81, v81
	s_waitcnt lgkmcnt(7)
	v_mfma_f32_32x32x16_bf16 v[148:163], v[172:175], v[104:107], v[148:163]
	ds_read_b64_tr_b16 v[234:235], v211 offset:16384
	ds_read_b64_tr_b16 v[236:237], v211 offset:17920
	v_exp_f32_e32 v82, v82
	v_exp_f32_e32 v83, v83
	v_add_f32_e32 v14, v14, v15
	v_add_f32_e32 v14, v14, v248
	s_waitcnt lgkmcnt(8)
	v_mfma_f32_32x32x16_bf16 v[148:163], v[214:217], v[108:111], v[148:163]
	ds_read_b64_tr_b16 v[238:239], v211 offset:16448
	ds_read_b64_tr_b16 v[240:241], v211 offset:17984
	v_add_f32_e32 v15, v80, v81
	v_add_f32_e32 v213, v82, v83
	v_exp_f32_e32 v84, v84
	v_exp_f32_e32 v85, v85
	s_waitcnt lgkmcnt(9)
	v_mfma_f32_32x32x16_bf16 v[148:163], v[218:221], v[112:115], v[148:163]
	v_exp_f32_e32 v86, v86
	v_exp_f32_e32 v87, v87
	v_add_f32_e32 v15, v15, v213
	v_add_f32_e32 v213, v84, v85
	s_waitcnt lgkmcnt(8)
	v_mfma_f32_32x32x16_bf16 v[148:163], v[222:225], v[116:119], v[148:163]
	v_add_f32_e32 v248, v86, v87
	v_cvt_pk_bf16_f32 v80, v80, v81
	v_cvt_pk_bf16_f32 v81, v82, v83
	v_cvt_pk_bf16_f32 v82, v84, v85
	v_cvt_pk_bf16_f32 v83, v86, v87
	s_waitcnt lgkmcnt(6)
	v_mfma_f32_32x32x16_bf16 v[32:47], v[226:229], v[64:67], v[32:47]
	ds_read_b64_tr_b16 v[226:227], v211 offset:19456
	ds_read_b64_tr_b16 v[228:229], v211 offset:20992
	s_cmp_lg_u32 s56, 0
	s_cbranch_scc1 .Lmla_mask0
.Lmla_maskret0:
	v_exp_f32_e32 v88, v88
	v_exp_f32_e32 v89, v89
	v_exp_f32_e32 v90, v90
	v_exp_f32_e32 v91, v91
	v_max3_f32 v251, v132, v133, v134
	v_max3_f32 v251, v251, v135, v136
	s_waitcnt lgkmcnt(6)
	v_mfma_f32_32x32x16_bf16 v[16:31], v[230:233], v[64:67], v[16:31]
	ds_read_b64_tr_b16 v[230:231], v211 offset:19520
	ds_read_b64_tr_b16 v[232:233], v211 offset:21056
	v_add_f32_e32 v213, v213, v248
	v_add_f32_e32 v15, v15, v213
	v_exp_f32_e32 v92, v92
	v_exp_f32_e32 v93, v93
	v_max3_f32 v251, v251, v137, v138
	v_max3_f32 v251, v251, v139, v140
	s_waitcnt lgkmcnt(6)
	v_mfma_f32_32x32x16_bf16 v[32:47], v[234:237], v[68:71], v[32:47]
	ds_read_b64_tr_b16 v[234:235], v211 offset:22528
	ds_read_b64_tr_b16 v[236:237], v211 offset:24064
	v_exp_f32_e32 v94, v94
	v_exp_f32_e32 v95, v95
	v_add_f32_e32 v213, v88, v89
	v_add_f32_e32 v248, v90, v91
	v_max3_f32 v251, v251, v141, v142
	v_max3_f32 v251, v251, v143, v144
	s_waitcnt lgkmcnt(6)
	v_mfma_f32_32x32x16_bf16 v[16:31], v[238:241], v[68:71], v[16:31]
	ds_read_b64_tr_b16 v[238:239], v211 offset:22592
	ds_read_b64_tr_b16 v[240:241], v211 offset:24128
	v_add_f32_e32 v249, v92, v93
	v_add_f32_e32 v250, v94, v95
	v_cvt_pk_bf16_f32 v84, v88, v89
	v_cvt_pk_bf16_f32 v85, v90, v91
	v_cvt_pk_bf16_f32 v86, v92, v93
	v_cvt_pk_bf16_f32 v87, v94, v95
	v_max3_f32 v251, v251, v145, v146
	v_max_f32_e32 v251, v251, v147
	s_waitcnt lgkmcnt(6)
	v_mfma_f32_32x32x16_bf16 v[32:47], v[226:229], v[80:83], v[32:47]
	v_add_f32_e32 v213, v213, v248
	v_add_f32_e32 v249, v249, v250
	v_add_f32_e32 v14, v14, v15
	v_max3_f32 v252, v148, v149, v150
	v_max3_f32 v252, v252, v151, v152
	v_max3_f32 v252, v252, v153, v154
	s_waitcnt lgkmcnt(4)
	v_mfma_f32_32x32x16_bf16 v[16:31], v[230:233], v[80:83], v[16:31]
	s_waitcnt vmcnt(3)
	ds_write_b128 v205, v[120:123] offset:0
	ds_write_b128 v206, v[124:127] offset:38912
	v_add_f32_e32 v213, v213, v249
	v_add_f32_e32 v14, v14, v213
	v_add_f32_e32 v209, v209, v14
	v_max3_f32 v252, v252, v155, v156
	v_max3_f32 v252, v252, v157, v158
	v_max3_f32 v252, v252, v159, v160
	s_waitcnt lgkmcnt(4)
	v_mfma_f32_32x32x16_bf16 v[32:47], v[234:237], v[84:87], v[32:47]
	v_max3_f32 v252, v252, v161, v162
	v_max_f32_e32 v252, v252, v163
	v_max_f32_e32 v251, v251, v252
	s_waitcnt lgkmcnt(2)
	v_mfma_f32_32x32x16_bf16 v[16:31], v[238:241], v[84:87], v[16:31]
	ds_write_b128 v207, v[128:131] offset:128
	v_cmp_lt_f32_e32 vcc, 0x41000000, v251
	s_cmp_lg_u32 s26, 0
	s_cbranch_scc0 .Lmla_nr0
	s_cbranch_vccnz .Lmla_rare0

.Lmla_end0:
.Lmla_it1:
	s_add_i32 s66, s65, 1
	s_add_i32 s42, s66, 3
	s_min_u32 s42, s42, s44
	s_lshl_b64 s[6:7], s[42:43], 17
	v_lshl_add_u64 v[242:243], v[190:191], 0, s[6:7]
	s_lshl_b64 s[6:7], s[42:43], 12
	v_lshl_add_u64 v[244:245], v[194:195], 0, s[6:7]
	s_add_i32 s42, s66, 2
	s_min_u32 s42, s42, s44
	s_lshl_b64 s[6:7], s[42:43], 17
	v_lshl_add_u64 v[246:247], v[192:193], 0, s[6:7]
	global_load_dwordx4 v[120:123], v[242:243], off
	global_load_dwordx4 v[124:127], v[246:247], off
	global_load_dwordx4 v[128:131], v[244:245], off
	s_cmp_ge_u32 s66, s45
	s_cbranch_scc1 .Lmla_skip1
	s_add_i32 s41, s66, 1
	s_cmp_ge_u32 s41, s64
	s_cselect_b32 s7, 1, 0
	s_cmp_lt_u32 s41, s45
	s_cselect_b32 s26, 1, 0
	s_and_b32 s56, s7, s26
	s_lshl_b32 s27, s41, 6
	ds_read_b128 v[164:167], v210 offset:0
	ds_read_b128 v[168:171], v210 offset:32
	ds_read_b128 v[172:175], v210 offset:64
	ds_read_b128 v[214:217], v210 offset:96
	ds_read_b128 v[218:221], v210 offset:128
	ds_read_b128 v[222:225], v210 offset:160
	v_exp_f32_e32 v132, v132
	v_exp_f32_e32 v133, v133
	v_exp_f32_e32 v134, v134
	v_exp_f32_e32 v135, v135
	s_waitcnt lgkmcnt(5)
	v_mfma_f32_32x32x16_bf16 v[64:79], v[164:167], v[96:99], v[48:63]
	ds_read_b128 v[164:167], v210 offset:6656
	v_add_f32_e32 v14, v132, v133
	v_add_f32_e32 v15, v134, v135
	v_exp_f32_e32 v136, v136
	v_exp_f32_e32 v137, v137
	s_waitcnt lgkmcnt(5)
	v_mfma_f32_32x32x16_bf16 v[64:79], v[168:171], v[100:103], v[64:79]
	ds_read_b128 v[168:171], v210 offset:6688
	v_exp_f32_e32 v138, v138
	v_exp_f32_e32 v139, v139
	v_add_f32_e32 v14, v14, v15
	v_add_f32_e32 v15, v136, v137
	s_waitcnt lgkmcnt(5)
	v_mfma_f32_32x32x16_bf16 v[64:79], v[172:175], v[104:107], v[64:79]
	ds_read_b128 v[172:175], v210 offset:6720
	v_add_f32_e32 v213, v138, v139
	v_cvt_pk_bf16_f32 v132, v132, v133
	v_cvt_pk_bf16_f32 v133, v134, v135
	v_cvt_pk_bf16_f32 v134, v136, v137
	v_cvt_pk_bf16_f32 v135, v138, v139
	s_waitcnt lgkmcnt(5)
	v_mfma_f32_32x32x16_bf16 v[64:79], v[214:217], v[108:111], v[64:79]
	ds_read_b128 v[214:217], v210 offset:6752
	v_exp_f32_e32 v140, v140
	v_exp_f32_e32 v141, v141
	v_exp_f32_e32 v142, v142
	v_exp_f32_e32 v143, v143
	s_waitcnt lgkmcnt(5)
	v_mfma_f32_32x32x16_bf16 v[64:79], v[218:221], v[112:115], v[64:79]
	ds_read_b128 v[218:221], v210 offset:6784
	v_add_f32_e32 v14, v14, v15
	v_add_f32_e32 v14, v14, v213
	v_exp_f32_e32 v144, v144
	v_exp_f32_e32 v145, v145
	s_waitcnt lgkmcnt(5)
	v_mfma_f32_32x32x16_bf16 v[64:79], v[222:225], v[116:119], v[64:79]
	ds_read_b128 v[222:225], v210 offset:6816
	v_exp_f32_e32 v146, v146
	v_exp_f32_e32 v147, v147
	v_add_f32_e32 v15, v140, v141
	v_add_f32_e32 v213, v142, v143
	s_waitcnt lgkmcnt(5)
	v_mfma_f32_32x32x16_bf16 v[80:95], v[164:167], v[96:99], v[48:63]
	ds_read_b64_tr_b16 v[226:227], v211 offset:38912
	ds_read_b64_tr_b16 v[228:229], v211 offset:40448
	v_add_f32_e32 v248, v144, v145
	v_add_f32_e32 v249, v146, v147
	v_cvt_pk_bf16_f32 v136, v140, v141
	v_cvt_pk_bf16_f32 v137, v142, v143
	v_cvt_pk_bf16_f32 v138, v144, v145
	v_cvt_pk_bf16_f32 v139, v146, v147
	s_waitcnt lgkmcnt(6)
	v_mfma_f32_32x32x16_bf16 v[80:95], v[168:171], v[100:103], v[80:95]
	ds_read_b64_tr_b16 v[230:231], v211 offset:38976
	ds_read_b64_tr_b16 v[232:233], v211 offset:40512
	v_add_f32_e32 v15, v15, v213
	v_add_f32_e32 v248, v248, v249
	v_exp_f32_e32 v148, v148
	v_exp_f32_e32 v149, v149
	s_waitcnt lgkmcnt(7)
	v_mfma_f32_32x32x16_bf16 v[80:95], v[172:175], v[104:107], v[80:95]
	ds_read_b64_tr_b16 v[234:235], v211 offset:41984
	ds_read_b64_tr_b16 v[236:237], v211 offset:43520
	v_exp_f32_e32 v150, v150
	v_exp_f32_e32 v151, v151
	v_add_f32_e32 v14, v14, v15
	v_add_f32_e32 v14, v14, v248
	s_waitcnt lgkmcnt(8)
	v_mfma_f32_32x32x16_bf16 v[80:95], v[214:217], v[108:111], v[80:95]
	ds_read_b64_tr_b16 v[238:239], v211 offset:42048
	ds_read_b64_tr_b16 v[240:241], v211 offset:43584
	v_add_f32_e32 v15, v148, v149
	v_add_f32_e32 v213, v150, v151
	v_exp_f32_e32 v152, v152
	v_exp_f32_e32 v153, v153
	s_waitcnt lgkmcnt(9)
	v_mfma_f32_32x32x16_bf16 v[80:95], v[218:221], v[112:115], v[80:95]
	v_exp_f32_e32 v154, v154
	v_exp_f32_e32 v155, v155
	v_add_f32_e32 v15, v15, v213
	v_add_f32_e32 v213, v152, v153
	s_waitcnt lgkmcnt(8)
	v_mfma_f32_32x32x16_bf16 v[80:95], v[222:225], v[116:119], v[80:95]
	v_add_f32_e32 v248, v154, v155
	v_cvt_pk_bf16_f32 v148, v148, v149
	v_cvt_pk_bf16_f32 v149, v150, v151
	v_cvt_pk_bf16_f32 v150, v152, v153
	v_cvt_pk_bf16_f32 v151, v154, v155
	s_waitcnt lgkmcnt(6)
	v_mfma_f32_32x32x16_bf16 v[32:47], v[226:229], v[132:135], v[32:47]
	ds_read_b64_tr_b16 v[226:227], v211 offset:45056
	ds_read_b64_tr_b16 v[228:229], v211 offset:46592
	s_cmp_lg_u32 s56, 0
	s_cbranch_scc1 .Lmla_mask1
.Lmla_maskret1:
	v_exp_f32_e32 v156, v156
	v_exp_f32_e32 v157, v157
	v_exp_f32_e32 v158, v158
	v_exp_f32_e32 v159, v159
	v_max3_f32 v251, v64, v65, v66
	v_max3_f32 v251, v251, v67, v68
	s_waitcnt lgkmcnt(6)
	v_mfma_f32_32x32x16_bf16 v[16:31], v[230:233], v[132:135], v[16:31]
	ds_read_b64_tr_b16 v[230:231], v211 offset:45120
	ds_read_b64_tr_b16 v[232:233], v211 offset:46656
	v_add_f32_e32 v213, v213, v248
	v_add_f32_e32 v15, v15, v213
	v_exp_f32_e32 v160, v160
	v_exp_f32_e32 v161, v161
	v_max3_f32 v251, v251, v69, v70
	v_max3_f32 v251, v251, v71, v72
	s_waitcnt lgkmcnt(6)
	v_mfma_f32_32x32x16_bf16 v[32:47], v[234:237], v[136:139], v[32:47]
	ds_read_b64_tr_b16 v[234:235], v211 offset:48128
	ds_read_b64_tr_b16 v[236:237], v211 offset:49664
	v_exp_f32_e32 v162, v162
	v_exp_f32_e32 v163, v163
	v_add_f32_e32 v213, v156, v157
	v_add_f32_e32 v248, v158, v159
	v_max3_f32 v251, v251, v73, v74
	v_max3_f32 v251, v251, v75, v76
	s_waitcnt lgkmcnt(6)
	v_mfma_f32_32x32x16_bf16 v[16:31], v[238:241], v[136:139], v[16:31]
	ds_read_b64_tr_b16 v[238:239], v211 offset:48192
	ds_read_b64_tr_b16 v[240:241], v211 offset:49728
	v_add_f32_e32 v249, v160, v161
	v_add_f32_e32 v250, v162, v163
	v_cvt_pk_bf16_f32 v152, v156, v157
	v_cvt_pk_bf16_f32 v153, v158, v159
	v_cvt_pk_bf16_f32 v154, v160, v161
	v_cvt_pk_bf16_f32 v155, v162, v163
	v_max3_f32 v251, v251, v77, v78
	v_max_f32_e32 v251, v251, v79
	s_waitcnt lgkmcnt(6)
	v_mfma_f32_32x32x16_bf16 v[32:47], v[226:229], v[148:151], v[32:47]
	v_add_f32_e32 v213, v213, v248
	v_add_f32_e32 v249, v249, v250
	v_add_f32_e32 v14, v14, v15
	v_max3_f32 v252, v80, v81, v82
	v_max3_f32 v252, v252, v83, v84
	v_max3_f32 v252, v252, v85, v86
	s_waitcnt lgkmcnt(4)
	v_mfma_f32_32x32x16_bf16 v[16:31], v[230:233], v[148:151], v[16:31]
	s_waitcnt vmcnt(3)
	ds_write_b128 v205, v[6:9] offset:25600
	ds_write_b128 v206, v[10:13] offset:13312
	v_add_f32_e32 v213, v213, v249
	v_add_f32_e32 v14, v14, v213
	v_add_f32_e32 v209, v209, v14
	v_max3_f32 v252, v252, v87, v88
	v_max3_f32 v252, v252, v89, v90
	v_max3_f32 v252, v252, v91, v92
	s_waitcnt lgkmcnt(4)
	v_mfma_f32_32x32x16_bf16 v[32:47], v[234:237], v[152:155], v[32:47]
	v_max3_f32 v252, v252, v93, v94
	v_max_f32_e32 v252, v252, v95
	v_max_f32_e32 v251, v251, v252
	s_waitcnt lgkmcnt(2)
	v_mfma_f32_32x32x16_bf16 v[16:31], v[238:241], v[152:155], v[16:31]
	ds_write_b128 v207, v[2:5] offset:25728
	v_cmp_lt_f32_e32 vcc, 0x41000000, v251
	s_cmp_lg_u32 s26, 0
	s_cbranch_scc0 .Lmla_nr1
	s_cbranch_vccnz .Lmla_rare1

.Lmla_rare0:
	s_nop 7
	s_nop 4
	v_mov_b32_e32 v252, v251
	s_nop 1
	v_permlane32_swap_b32_e32 v251, v252
	v_max_f32_e32 v251, v251, v252
	v_max_f32_e32 v253, 0, v251
	v_add_f32_e32 v212, v212, v253
	v_exp_f32_e64 v252, -v253
	v_xor_b32_e32 v48, 0x80000000, v212
	v_sub_f32_e32 v132, v132, v253
	v_sub_f32_e32 v133, v133, v253
	v_sub_f32_e32 v134, v134, v253
	v_sub_f32_e32 v135, v135, v253
	v_sub_f32_e32 v136, v136, v253
	v_sub_f32_e32 v137, v137, v253
	v_sub_f32_e32 v138, v138, v253
	v_sub_f32_e32 v139, v139, v253
	v_sub_f32_e32 v140, v140, v253
	v_sub_f32_e32 v141, v141, v253
	v_sub_f32_e32 v142, v142, v253
	v_sub_f32_e32 v143, v143, v253
	v_sub_f32_e32 v144, v144, v253
	v_sub_f32_e32 v145, v145, v253
	v_sub_f32_e32 v146, v146, v253
	v_sub_f32_e32 v147, v147, v253
	v_sub_f32_e32 v148, v148, v253
	v_sub_f32_e32 v149, v149, v253
	v_sub_f32_e32 v150, v150, v253
	v_sub_f32_e32 v151, v151, v253
	v_sub_f32_e32 v152, v152, v253
	v_sub_f32_e32 v153, v153, v253
	v_sub_f32_e32 v154, v154, v253
	v_sub_f32_e32 v155, v155, v253
	v_sub_f32_e32 v156, v156, v253
	v_sub_f32_e32 v157, v157, v253
	v_sub_f32_e32 v158, v158, v253
	v_sub_f32_e32 v159, v159, v253
	v_sub_f32_e32 v160, v160, v253
	v_sub_f32_e32 v161, v161, v253
	v_sub_f32_e32 v162, v162, v253
	v_sub_f32_e32 v163, v163, v253
	v_mov_b32_e32 v49, v48
	v_mov_b32_e32 v50, v48
	v_mov_b32_e32 v51, v48
	v_mov_b32_e32 v52, v48
	v_mov_b32_e32 v53, v48
	v_mov_b32_e32 v54, v48
	v_mov_b32_e32 v55, v48
	v_mov_b32_e32 v56, v48
	v_mov_b32_e32 v57, v48
	v_mov_b32_e32 v58, v48
	v_mov_b32_e32 v59, v48
	v_mov_b32_e32 v60, v48
	v_mov_b32_e32 v61, v48
	v_mov_b32_e32 v62, v48
	v_mov_b32_e32 v63, v48
	v_mul_f32_e32 v32, v32, v252
	v_mul_f32_e32 v33, v33, v252
	v_mul_f32_e32 v34, v34, v252
	v_mul_f32_e32 v35, v35, v252
	v_mul_f32_e32 v36, v36, v252
	v_mul_f32_e32 v37, v37, v252
	v_mul_f32_e32 v38, v38, v252
	v_mul_f32_e32 v39, v39, v252
	v_mul_f32_e32 v40, v40, v252
	v_mul_f32_e32 v41, v41, v252
	v_mul_f32_e32 v42, v42, v252
	v_mul_f32_e32 v43, v43, v252
	v_mul_f32_e32 v44, v44, v252
	v_mul_f32_e32 v45, v45, v252
	v_mul_f32_e32 v46, v46, v252
	v_mul_f32_e32 v47, v47, v252
	v_mul_f32_e32 v16, v16, v252
	v_mul_f32_e32 v17, v17, v252
	v_mul_f32_e32 v18, v18, v252
	v_mul_f32_e32 v19, v19, v252
	v_mul_f32_e32 v20, v20, v252
	v_mul_f32_e32 v21, v21, v252
	v_mul_f32_e32 v22, v22, v252
	v_mul_f32_e32 v23, v23, v252
	v_mul_f32_e32 v24, v24, v252
	v_mul_f32_e32 v25, v25, v252
	v_mul_f32_e32 v26, v26, v252
	v_mul_f32_e32 v27, v27, v252
	v_mul_f32_e32 v28, v28, v252
	v_mul_f32_e32 v29, v29, v252
	v_mul_f32_e32 v30, v30, v252
	v_mul_f32_e32 v31, v31, v252
	v_mul_f32_e32 v209, v209, v252
	s_branch .Lmla_nr0

.Lmla_rare1:
	s_nop 7
	s_nop 4
	v_mov_b32_e32 v252, v251
	s_nop 1
	v_permlane32_swap_b32_e32 v251, v252
	v_max_f32_e32 v251, v251, v252
	v_max_f32_e32 v253, 0, v251
	v_add_f32_e32 v212, v212, v253
	v_exp_f32_e64 v252, -v253
	v_xor_b32_e32 v48, 0x80000000, v212
	v_sub_f32_e32 v64, v64, v253
	v_sub_f32_e32 v65, v65, v253
	v_sub_f32_e32 v66, v66, v253
	v_sub_f32_e32 v67, v67, v253
	v_sub_f32_e32 v68, v68, v253
	v_sub_f32_e32 v69, v69, v253
	v_sub_f32_e32 v70, v70, v253
	v_sub_f32_e32 v71, v71, v253
	v_sub_f32_e32 v72, v72, v253
	v_sub_f32_e32 v73, v73, v253
	v_sub_f32_e32 v74, v74, v253
	v_sub_f32_e32 v75, v75, v253
	v_sub_f32_e32 v76, v76, v253
	v_sub_f32_e32 v77, v77, v253
	v_sub_f32_e32 v78, v78, v253
	v_sub_f32_e32 v79, v79, v253
	v_sub_f32_e32 v80, v80, v253
	v_sub_f32_e32 v81, v81, v253
	v_sub_f32_e32 v82, v82, v253
	v_sub_f32_e32 v83, v83, v253
	v_sub_f32_e32 v84, v84, v253
	v_sub_f32_e32 v85, v85, v253
	v_sub_f32_e32 v86, v86, v253
	v_sub_f32_e32 v87, v87, v253
	v_sub_f32_e32 v88, v88, v253
	v_sub_f32_e32 v89, v89, v253
	v_sub_f32_e32 v90, v90, v253
	v_sub_f32_e32 v91, v91, v253
	v_sub_f32_e32 v92, v92, v253
	v_sub_f32_e32 v93, v93, v253
	v_sub_f32_e32 v94, v94, v253
	v_sub_f32_e32 v95, v95, v253
	v_mov_b32_e32 v49, v48
	v_mov_b32_e32 v50, v48
	v_mov_b32_e32 v51, v48
	v_mov_b32_e32 v52, v48
	v_mov_b32_e32 v53, v48
	v_mov_b32_e32 v54, v48
	v_mov_b32_e32 v55, v48
	v_mov_b32_e32 v56, v48
	v_mov_b32_e32 v57, v48
	v_mov_b32_e32 v58, v48
	v_mov_b32_e32 v59, v48
	v_mov_b32_e32 v60, v48
	v_mov_b32_e32 v61, v48
	v_mov_b32_e32 v62, v48
	v_mov_b32_e32 v63, v48
	v_mul_f32_e32 v32, v32, v252
	v_mul_f32_e32 v33, v33, v252
	v_mul_f32_e32 v34, v34, v252
	v_mul_f32_e32 v35, v35, v252
	v_mul_f32_e32 v36, v36, v252
	v_mul_f32_e32 v37, v37, v252
	v_mul_f32_e32 v38, v38, v252
	v_mul_f32_e32 v39, v39, v252
	v_mul_f32_e32 v40, v40, v252
	v_mul_f32_e32 v41, v41, v252
	v_mul_f32_e32 v42, v42, v252
	v_mul_f32_e32 v43, v43, v252
	v_mul_f32_e32 v44, v44, v252
	v_mul_f32_e32 v45, v45, v252
	v_mul_f32_e32 v46, v46, v252
	v_mul_f32_e32 v47, v47, v252
	v_mul_f32_e32 v16, v16, v252
	v_mul_f32_e32 v17, v17, v252
	v_mul_f32_e32 v18, v18, v252
	v_mul_f32_e32 v19, v19, v252
	v_mul_f32_e32 v20, v20, v252
	v_mul_f32_e32 v21, v21, v252
	v_mul_f32_e32 v22, v22, v252
	v_mul_f32_e32 v23, v23, v252
	v_mul_f32_e32 v24, v24, v252
	v_mul_f32_e32 v25, v25, v252
	v_mul_f32_e32 v26, v26, v252
	v_mul_f32_e32 v27, v27, v252
	v_mul_f32_e32 v28, v28, v252
	v_mul_f32_e32 v29, v29, v252
	v_mul_f32_e32 v30, v30, v252
	v_mul_f32_e32 v31, v31, v252
	v_mul_f32_e32 v209, v209, v252
	s_branch .Lmla_nr1
